# hand-written conv loop: loop-invariant weights hoisted, single wait per iteration
# speedup vs baseline: 1.0214x; 1.0050x over previous
.LBB0_463:
	s_or_b64 exec, exec, s[0:1]
	s_waitcnt lgkmcnt(0)
	s_barrier
	v_mbcnt_lo_u32_b32 v0, -1, 0
	v_mbcnt_hi_u32_b32 v0, -1, v0
	v_readlane_b32 s0, v252, 1
	v_or_b32_e32 v1, s33, v0
	s_nop 0
	v_add_u32_e32 v0, s0, v1
	s_mov_b32 s0, 0x400000
	v_cmp_gt_i32_e32 vcc, s0, v0
	s_and_saveexec_b64 s[4:5], vcc
	v_readlane_b32 s40, v255, 11
	v_readlane_b32 s41, v255, 12
	v_readlane_b32 s39, v254, 40
	s_movk_i32 s45, 0x2000
	s_movk_i32 s56, 0x3000
	s_cbranch_execz .LBB0_466
	v_readlane_b32 s42, v255, 19
	v_readlane_b32 s43, v255, 20
	v_readlane_b32 s12, v252, 6
	s_lshl_b64 s[0:1], s[42:43], 14
	v_readlane_b32 s14, v252, 8
	v_readlane_b32 s15, v252, 9
	s_add_u32 s46, s14, s0
	v_readlane_b32 s16, v252, 10
	s_addc_u32 s47, s15, s1
	s_lshl_b64 s[0:1], s[42:43], 12
	v_readlane_b32 s17, v252, 11
	s_add_u32 s48, s16, s0
	v_readlane_b32 s0, v254, 39
	s_addc_u32 s49, s17, s1
	s_mov_b64 s[50:51], 0
	v_lshl_add_u32 v1, v1, 3, s0
	v_readlane_b32 s13, v252, 7
	v_readlane_b32 s18, v252, 12
	v_readlane_b32 s19, v252, 13
	v_readlane_b32 s20, v252, 14
	v_readlane_b32 s21, v252, 15
	v_readlane_b32 s22, v252, 16
	v_readlane_b32 s23, v252, 17
	v_readlane_b32 s24, v252, 18
	v_readlane_b32 s25, v252, 19
	v_readlane_b32 s26, v252, 20
	v_readlane_b32 s27, v252, 21
	v_and_b32_e32 v2, 0x3f8, v1
	v_lshlrev_b32_e32 v160, 1, v2
	v_lshlrev_b32_e32 v34, 2, v2
	v_mov_b32_e32 v35, v161
	v_lshl_add_u64 v[26:27], s[46:47], 0, v[34:35]
	global_load_dwordx4 v[100:103], v[26:27], off
	global_load_dwordx4 v[104:107], v[26:27], off offset:16
	s_mov_b64 s[0:1], 0x1000
	v_lshl_add_u64 v[28:29], v[26:27], 0, s[0:1]
	global_load_dwordx4 v[108:111], v[28:29], off
	global_load_dwordx4 v[112:115], v[28:29], off offset:16
	s_mov_b64 s[0:1], 0x2000
	v_lshl_add_u64 v[28:29], v[26:27], 0, s[0:1]
	global_load_dwordx4 v[116:119], v[28:29], off
	global_load_dwordx4 v[120:123], v[28:29], off offset:16
	s_mov_b64 s[0:1], 0x3000
	v_lshl_add_u64 v[28:29], v[26:27], 0, s[0:1]
	global_load_dwordx4 v[124:127], v[28:29], off
	global_load_dwordx4 v[128:131], v[28:29], off offset:16
	global_load_dwordx4 v[132:135], v34, s[48:49]
	global_load_dwordx4 v[136:139], v34, s[48:49] offset:16
	v_lshl_add_u64 v[24:25], s[40:41], 0, v[160:161]
	v_lshl_add_u64 v[30:31], s[96:97], 0, v[160:161]
	s_waitcnt vmcnt(0)
.LBB0_465:
	v_ashrrev_i32_e32 v22, 7, v0
	v_and_b32_e32 v23, 0xfff, v22
	v_mov_b32_e32 v32, v22
	v_ashrrev_i32_e32 v33, 31, v22
	v_lshlrev_b64 v[36:37], 11, v[32:33]
	v_lshl_add_u64 v[38:39], v[24:25], 0, v[36:37]
	global_load_dwordx4 v[40:43], v[38:39], off offset:-4096
	global_load_dwordx4 v[44:47], v[38:39], off offset:-2048
	global_load_dwordx4 v[48:51], v[38:39], off
	global_load_dwordx4 v[52:55], v[38:39], off offset:2048
	v_cmp_lt_u32_e64 s[0:1], 1, v23
	v_cmp_ne_u32_e64 s[100:101], 0, v23
	v_cmp_ne_u32_e32 vcc, 0xfff, v23
	v_lshl_add_u64 v[72:73], v[30:31], 0, v[36:37]
	v_add_u32_e32 v0, s59, v0
	s_waitcnt vmcnt(0)
	v_cndmask_b32_e64 v40, 0, v40, s[0:1]
	v_cndmask_b32_e64 v41, 0, v41, s[0:1]
	v_cndmask_b32_e64 v42, 0, v42, s[0:1]
	v_cndmask_b32_e64 v43, 0, v43, s[0:1]
	v_cndmask_b32_e64 v44, 0, v44, s[100:101]
	v_cndmask_b32_e64 v45, 0, v45, s[100:101]
	v_cndmask_b32_e64 v46, 0, v46, s[100:101]
	v_cndmask_b32_e64 v47, 0, v47, s[100:101]
	v_cndmask_b32_e32 v52, 0, v52, vcc
	v_cndmask_b32_e32 v53, 0, v53, vcc
	v_cndmask_b32_e32 v54, 0, v54, vcc
	v_cndmask_b32_e32 v55, 0, v55, vcc
	v_lshlrev_b32_e32 v56, 16, v40
	v_mul_f32_e32 v56, v100, v56
	v_add_f32_e32 v60, v56, v132
	v_lshlrev_b32_e32 v56, 16, v44
	v_mul_f32_e32 v56, v108, v56
	v_add_f32_e32 v60, v56, v60
	v_lshlrev_b32_e32 v56, 16, v48
	v_mul_f32_e32 v56, v116, v56
	v_add_f32_e32 v60, v56, v60
	v_lshlrev_b32_e32 v56, 16, v52
	v_mul_f32_e32 v56, v124, v56
	v_add_f32_e32 v60, v56, v60
	v_and_b32_e32 v56, 0xffff0000, v40
	v_mul_f32_e32 v56, v101, v56
	v_add_f32_e32 v61, v56, v133
	v_and_b32_e32 v56, 0xffff0000, v44
	v_mul_f32_e32 v56, v109, v56
	v_add_f32_e32 v61, v56, v61
	v_and_b32_e32 v56, 0xffff0000, v48
	v_mul_f32_e32 v56, v117, v56
	v_add_f32_e32 v61, v56, v61
	v_and_b32_e32 v56, 0xffff0000, v52
	v_mul_f32_e32 v56, v125, v56
	v_add_f32_e32 v61, v56, v61
	v_lshlrev_b32_e32 v56, 16, v41
	v_mul_f32_e32 v56, v102, v56
	v_add_f32_e32 v62, v56, v134
	v_lshlrev_b32_e32 v56, 16, v45
	v_mul_f32_e32 v56, v110, v56
	v_add_f32_e32 v62, v56, v62
	v_lshlrev_b32_e32 v56, 16, v49
	v_mul_f32_e32 v56, v118, v56
	v_add_f32_e32 v62, v56, v62
	v_lshlrev_b32_e32 v56, 16, v53
	v_mul_f32_e32 v56, v126, v56
	v_add_f32_e32 v62, v56, v62
	v_and_b32_e32 v56, 0xffff0000, v41
	v_mul_f32_e32 v56, v103, v56
	v_add_f32_e32 v63, v56, v135
	v_and_b32_e32 v56, 0xffff0000, v45
	v_mul_f32_e32 v56, v111, v56
	v_add_f32_e32 v63, v56, v63
	v_and_b32_e32 v56, 0xffff0000, v49
	v_mul_f32_e32 v56, v119, v56
	v_add_f32_e32 v63, v56, v63
	v_and_b32_e32 v56, 0xffff0000, v53
	v_mul_f32_e32 v56, v127, v56
	v_add_f32_e32 v63, v56, v63
	v_lshlrev_b32_e32 v56, 16, v42
	v_mul_f32_e32 v56, v104, v56
	v_add_f32_e32 v64, v56, v136
	v_lshlrev_b32_e32 v56, 16, v46
	v_mul_f32_e32 v56, v112, v56
	v_add_f32_e32 v64, v56, v64
	v_lshlrev_b32_e32 v56, 16, v50
	v_mul_f32_e32 v56, v120, v56
	v_add_f32_e32 v64, v56, v64
	v_lshlrev_b32_e32 v56, 16, v54
	v_mul_f32_e32 v56, v128, v56
	v_add_f32_e32 v64, v56, v64
	v_and_b32_e32 v56, 0xffff0000, v42
	v_mul_f32_e32 v56, v105, v56
	v_add_f32_e32 v65, v56, v137
	v_and_b32_e32 v56, 0xffff0000, v46
	v_mul_f32_e32 v56, v113, v56
	v_add_f32_e32 v65, v56, v65
	v_and_b32_e32 v56, 0xffff0000, v50
	v_mul_f32_e32 v56, v121, v56
	v_add_f32_e32 v65, v56, v65
	v_and_b32_e32 v56, 0xffff0000, v54
	v_mul_f32_e32 v56, v129, v56
	v_add_f32_e32 v65, v56, v65
	v_lshlrev_b32_e32 v56, 16, v43
	v_mul_f32_e32 v56, v106, v56
	v_add_f32_e32 v66, v56, v138
	v_lshlrev_b32_e32 v56, 16, v47
	v_mul_f32_e32 v56, v114, v56
	v_add_f32_e32 v66, v56, v66
	v_lshlrev_b32_e32 v56, 16, v51
	v_mul_f32_e32 v56, v122, v56
	v_add_f32_e32 v66, v56, v66
	v_lshlrev_b32_e32 v56, 16, v55
	v_mul_f32_e32 v56, v130, v56
	v_add_f32_e32 v66, v56, v66
	v_and_b32_e32 v56, 0xffff0000, v43
	v_mul_f32_e32 v56, v107, v56
	v_add_f32_e32 v67, v56, v139
	v_and_b32_e32 v56, 0xffff0000, v47
	v_mul_f32_e32 v56, v115, v56
	v_add_f32_e32 v67, v56, v67
	v_and_b32_e32 v56, 0xffff0000, v51
	v_mul_f32_e32 v56, v123, v56
	v_add_f32_e32 v67, v56, v67
	v_and_b32_e32 v56, 0xffff0000, v55
	v_mul_f32_e32 v56, v131, v56
	v_add_f32_e32 v67, v56, v67
	v_cvt_pk_bf16_f32 v68, v60, v61
	v_cvt_pk_bf16_f32 v69, v62, v63
	v_cvt_pk_bf16_f32 v70, v64, v65
	v_cvt_pk_bf16_f32 v71, v66, v67
	v_cmp_lt_i32_e32 vcc, 0x3fffff, v0
	global_store_dwordx4 v[72:73], v[68:71], off
	s_or_b64 s[50:51], vcc, s[50:51]
	s_andn2_b64 exec, exec, s[50:51]
	s_cbranch_execnz .LBB0_465

	.amdhsa_kernel _Z8mega_fwd6Params
		.amdhsa_group_segment_fixed_size 0
		.amdhsa_private_segment_fixed_size 0
		.amdhsa_kernarg_size 456
		.amdhsa_user_sgpr_count 2
		.amdhsa_user_sgpr_dispatch_ptr 0
		.amdhsa_user_sgpr_queue_ptr 0
		.amdhsa_user_sgpr_kernarg_segment_ptr 1
		.amdhsa_user_sgpr_dispatch_id 0
		.amdhsa_user_sgpr_kernarg_preload_length 0
		.amdhsa_user_sgpr_kernarg_preload_offset 0
		.amdhsa_user_sgpr_private_segment_size 0
		.amdhsa_uses_dynamic_stack 0
		.amdhsa_enable_private_segment 0
		.amdhsa_system_sgpr_workgroup_id_x 1
		.amdhsa_system_sgpr_workgroup_id_y 0
		.amdhsa_system_sgpr_workgroup_id_z 0
		.amdhsa_system_sgpr_workgroup_info 0
		.amdhsa_system_vgpr_workitem_id 2
		.amdhsa_next_free_vgpr 256
		.amdhsa_next_free_sgpr 102
		.amdhsa_accum_offset 256
		.amdhsa_reserve_vcc 1
		.amdhsa_float_round_mode_32 0
		.amdhsa_float_round_mode_16_64 0
		.amdhsa_float_denorm_mode_32 3
		.amdhsa_float_denorm_mode_16_64 3
		.amdhsa_dx10_clamp 1
		.amdhsa_ieee_mode 1
		.amdhsa_fp16_overflow 0
		.amdhsa_tg_split 0
		.amdhsa_exception_fp_ieee_invalid_op 0
		.amdhsa_exception_fp_denorm_src 0
		.amdhsa_exception_fp_ieee_div_zero 0
		.amdhsa_exception_fp_ieee_overflow 0
		.amdhsa_exception_fp_ieee_underflow 0
		.amdhsa_exception_fp_ieee_inexact 0
		.amdhsa_exception_int_div_zero 0
	.end_amdhsa_kernel

amdhsa.kernels:
  - .agpr_count:     0
    .args:
      - .offset:         0
        .size:           200
        .value_kind:     by_value
      - .offset:         200
        .size:           4
        .value_kind:     hidden_block_count_x
      - .offset:         204
        .size:           4
        .value_kind:     hidden_block_count_y
      - .offset:         208
        .size:           4
        .value_kind:     hidden_block_count_z
      - .offset:         212
        .size:           2
        .value_kind:     hidden_group_size_x
      - .offset:         214
        .size:           2
        .value_kind:     hidden_group_size_y
      - .offset:         216
        .size:           2
        .value_kind:     hidden_group_size_z
      - .offset:         218
        .size:           2
        .value_kind:     hidden_remainder_x
      - .offset:         220
        .size:           2
        .value_kind:     hidden_remainder_y
      - .offset:         222
        .size:           2
        .value_kind:     hidden_remainder_z
      - .offset:         240
        .size:           8
        .value_kind:     hidden_global_offset_x
      - .offset:         248
        .size:           8
        .value_kind:     hidden_global_offset_y
      - .offset:         256
        .size:           8
        .value_kind:     hidden_global_offset_z
      - .offset:         264
        .size:           2
        .value_kind:     hidden_grid_dims
      - .offset:         288
        .size:           8
        .value_kind:     hidden_multigrid_sync_arg
      - .offset:         320
        .size:           4
        .value_kind:     hidden_dynamic_lds_size
    .group_segment_fixed_size: 0
    .kernarg_segment_align: 8
    .kernarg_segment_size: 456
    .language:       OpenCL C
    .language_version:
      - 2
      - 0
    .max_flat_workgroup_size: 512
    .name:           _Z8mega_fwd6Params
    .private_segment_fixed_size: 0
    .sgpr_count:     108
    .sgpr_spill_count: 797
    .symbol:         _Z8mega_fwd6Params.kd
    .uniform_work_group_size: 1
    .uses_dynamic_stack: false
    .vgpr_count:     256
    .vgpr_spill_count: 0
    .wavefront_size: 64
